# lean in-proj epilogue: lane = 8 columns, 16-byte stores (8 rows x 128 B per store), half the store instructions
# speedup vs baseline: 1.0065x; 1.0065x over previous
.LBB0_220:
	s_cmp_gt_i32 s7, 0
	s_waitcnt vmcnt(6)
	s_cselect_b32 s8, -1, 2
	s_mul_i32 s9, s7, 0x6000
	s_waitcnt lgkmcnt(0)
	s_add_i32 s8, s8, s7
	v_add_u32_e32 v139, s9, v224
	v_add_u32_e32 v0, s9, v223
	s_mulk_i32 s8, 0x6000
	v_add_u32_e32 v154, v139, v228
	s_barrier
	v_lshl_add_u64 v[170:171], v[144:145], 0, s[2:3]
	v_add_u32_e32 v141, s8, v221
	v_lshl_add_u64 v[174:175], v[142:143], 0, s[2:3]
	v_add_u32_e32 v182, s8, v222
	v_add_u32_e32 v166, v0, v228
	ds_read_b128 v[146:149], v166
	ds_read_b128 v[150:153], v154
	ds_read_b128 v[154:157], v154 offset:2048
	v_lshl_add_u64 v[172:173], v[170:171], 0, s[88:89]
	v_lshl_add_u64 v[176:177], v[174:175], 0, s[88:89]
	v_add_u32_e32 v183, 0x4000, v182
	v_lshl_add_u64 v[178:179], v[170:171], 0, s[90:91]
	v_add_u32_e32 v184, 0x400, v141
	v_lshl_add_u64 v[180:181], v[170:171], 0, s[78:79]
	v_add_u32_e32 v185, 0x800, v141
	ds_read_b128 v[158:161], v166 offset:2048
	ds_read_b128 v[162:165], v166 offset:4096
	ds_read_b128 v[166:169], v166 offset:6144
	s_waitcnt lgkmcnt(3)
	s_setprio 1
	v_mfma_f32_32x32x16_bf16 v[114:129], v[146:149], v[150:153], v[114:129]
	v_mfma_f32_32x32x16_bf16 v[98:113], v[146:149], v[154:157], v[98:113]
	v_readfirstlane_b32 s8, v141
	s_mov_b32 m0, s8
	s_nop 0
	global_load_lds_dwordx4 v[172:173], off
	s_waitcnt lgkmcnt(2)
	v_mfma_f32_32x32x16_bf16 v[82:97], v[158:161], v[150:153], v[82:97]
	v_mfma_f32_32x32x16_bf16 v[66:81], v[158:161], v[154:157], v[66:81]
	v_readfirstlane_b32 s8, v184
	s_mov_b32 m0, s8
	s_nop 0
	global_load_lds_dwordx4 v[178:179], off
	s_waitcnt lgkmcnt(1)
	v_mfma_f32_32x32x16_bf16 v[50:65], v[162:165], v[150:153], v[50:65]
	v_mfma_f32_32x32x16_bf16 v[34:49], v[162:165], v[154:157], v[34:49]
	v_readfirstlane_b32 s8, v185
	s_mov_b32 m0, s8
	s_nop 0
	global_load_lds_dwordx4 v[180:181], off
	s_waitcnt lgkmcnt(0)
	v_mfma_f32_32x32x16_bf16 v[18:33], v[166:169], v[150:153], v[18:33]
	v_mfma_f32_32x32x16_bf16 v[2:17], v[166:169], v[154:157], v[2:17]
	s_setprio 0
	v_add_u32_e32 v0, v0, v229
	v_add_u32_e32 v139, v139, v229
	ds_read_b128 v[146:149], v0
	ds_read_b128 v[150:153], v139
	ds_read_b128 v[154:157], v139 offset:2048
	ds_read_b128 v[158:161], v0 offset:2048
	ds_read_b128 v[162:165], v0 offset:4096
	ds_read_b128 v[166:169], v0 offset:6144
	s_waitcnt lgkmcnt(3)
	s_setprio 1
	v_mfma_f32_32x32x16_bf16 v[114:129], v[146:149], v[150:153], v[114:129]
	v_mfma_f32_32x32x16_bf16 v[98:113], v[146:149], v[154:157], v[98:113]
	v_add_u32_e32 v0, 0xc00, v141
	v_lshl_add_u64 v[146:147], v[170:171], 0, s[76:77]
	v_readfirstlane_b32 s8, v0
	s_mov_b32 m0, s8
	s_nop 0
	global_load_lds_dwordx4 v[146:147], off
	s_waitcnt lgkmcnt(2)
	v_mfma_f32_32x32x16_bf16 v[82:97], v[158:161], v[150:153], v[82:97]
	v_mfma_f32_32x32x16_bf16 v[66:81], v[158:161], v[154:157], v[66:81]
	v_readfirstlane_b32 s8, v183
	s_mov_b32 m0, s8
	s_nop 0
	global_load_lds_dwordx4 v[176:177], off
	s_waitcnt lgkmcnt(1)
	v_mfma_f32_32x32x16_bf16 v[50:65], v[162:165], v[150:153], v[50:65]
	v_mfma_f32_32x32x16_bf16 v[34:49], v[162:165], v[154:157], v[34:49]
	v_add_u32_e32 v0, 0x4400, v182
	v_lshl_add_u64 v[146:147], v[174:175], 0, s[90:91]
	v_readfirstlane_b32 s8, v0
	s_mov_b32 m0, s8
	s_nop 0
	global_load_lds_dwordx4 v[146:147], off
	s_waitcnt lgkmcnt(0)
	v_mfma_f32_32x32x16_bf16 v[18:33], v[166:169], v[150:153], v[18:33]
	v_mfma_f32_32x32x16_bf16 v[2:17], v[166:169], v[154:157], v[2:17]
	s_setprio 0
	s_add_i32 s8, s7, 1
	s_cmp_lt_i32 s7, 2
	s_cselect_b32 s7, s8, 0
	s_add_u32 s2, s2, 0x80
	s_addc_u32 s3, s3, 0
	s_cmpk_eq_i32 s2, 0xf00
	s_cbranch_scc0 .LBB0_220
	s_waitcnt vmcnt(6)
	s_mul_i32 s2, s7, 0x6000
	s_waitcnt lgkmcnt(0)
	v_add_u32_e32 v139, s2, v224
	v_add_u32_e32 v0, s2, v223
	v_add_u32_e32 v150, v139, v228
	s_barrier
	v_add_u32_e32 v141, v0, v228
	ds_read_b128 v[142:145], v141
	ds_read_b128 v[146:149], v150
	ds_read_b128 v[150:153], v150 offset:2048
	ds_read_b128 v[154:157], v141 offset:2048
	ds_read_b128 v[158:161], v141 offset:4096
	ds_read_b128 v[162:165], v141 offset:6144
	s_waitcnt lgkmcnt(3)
	s_setprio 1
	v_mfma_f32_32x32x16_bf16 v[114:129], v[142:145], v[146:149], v[114:129]
	v_mfma_f32_32x32x16_bf16 v[98:113], v[142:145], v[150:153], v[98:113]
	s_waitcnt lgkmcnt(2)
	v_mfma_f32_32x32x16_bf16 v[82:97], v[154:157], v[146:149], v[82:97]
	v_mfma_f32_32x32x16_bf16 v[66:81], v[154:157], v[150:153], v[66:81]
	s_waitcnt lgkmcnt(1)
	v_mfma_f32_32x32x16_bf16 v[50:65], v[158:161], v[146:149], v[50:65]
	v_mfma_f32_32x32x16_bf16 v[34:49], v[158:161], v[150:153], v[34:49]
	s_waitcnt lgkmcnt(0)
	v_mfma_f32_32x32x16_bf16 v[18:33], v[162:165], v[146:149], v[18:33]
	v_mfma_f32_32x32x16_bf16 v[2:17], v[162:165], v[150:153], v[2:17]
	s_setprio 0
	v_add_u32_e32 v0, v0, v229
	v_add_u32_e32 v139, v139, v229
	ds_read_b128 v[142:145], v0
	ds_read_b128 v[146:149], v139
	ds_read_b128 v[150:153], v139 offset:2048
	ds_read_b128 v[154:157], v0 offset:2048
	ds_read_b128 v[158:161], v0 offset:4096
	ds_read_b128 v[162:165], v0 offset:6144
	s_waitcnt lgkmcnt(3)
	s_setprio 1
	v_mfma_f32_32x32x16_bf16 v[114:129], v[142:145], v[146:149], v[114:129]
	v_mfma_f32_32x32x16_bf16 v[98:113], v[142:145], v[150:153], v[98:113]
	s_waitcnt lgkmcnt(2)
	v_mfma_f32_32x32x16_bf16 v[82:97], v[154:157], v[146:149], v[82:97]
	v_mfma_f32_32x32x16_bf16 v[66:81], v[154:157], v[150:153], v[66:81]
	s_waitcnt lgkmcnt(1)
	v_mfma_f32_32x32x16_bf16 v[50:65], v[158:161], v[146:149], v[50:65]
	v_mfma_f32_32x32x16_bf16 v[34:49], v[158:161], v[150:153], v[34:49]
	s_waitcnt lgkmcnt(0)
	v_mfma_f32_32x32x16_bf16 v[18:33], v[162:165], v[146:149], v[18:33]
	v_mfma_f32_32x32x16_bf16 v[2:17], v[162:165], v[150:153], v[2:17]
	s_setprio 0
	s_waitcnt vmcnt(0)
	s_waitcnt lgkmcnt(0)
	s_barrier
	ds_read_b128 v[142:145], v232
	ds_read_b128 v[146:149], v233
	ds_read_b128 v[150:153], v233 offset:2048
	ds_read_b128 v[154:157], v232 offset:2048
	ds_read_b128 v[158:161], v232 offset:4096
	ds_read_b128 v[162:165], v232 offset:6144
	s_waitcnt lgkmcnt(3)
	s_setprio 1
	v_mfma_f32_32x32x16_bf16 v[114:129], v[142:145], v[146:149], v[114:129]
	v_mfma_f32_32x32x16_bf16 v[98:113], v[142:145], v[150:153], v[98:113]
	s_waitcnt lgkmcnt(2)
	v_mfma_f32_32x32x16_bf16 v[82:97], v[154:157], v[146:149], v[82:97]
	v_mfma_f32_32x32x16_bf16 v[66:81], v[154:157], v[150:153], v[66:81]
	s_waitcnt lgkmcnt(1)
	v_mfma_f32_32x32x16_bf16 v[50:65], v[158:161], v[146:149], v[50:65]
	v_mfma_f32_32x32x16_bf16 v[34:49], v[158:161], v[150:153], v[34:49]
	s_waitcnt lgkmcnt(0)
	v_mfma_f32_32x32x16_bf16 v[18:33], v[162:165], v[146:149], v[18:33]
	v_mfma_f32_32x32x16_bf16 v[2:17], v[162:165], v[150:153], v[2:17]
	s_setprio 0
	ds_read_b128 v[142:145], v234
	ds_read_b128 v[146:149], v235
	ds_read_b128 v[150:153], v235 offset:2048
	ds_read_b128 v[154:157], v234 offset:2048
	ds_read_b128 v[158:161], v234 offset:4096
	ds_read_b128 v[162:165], v234 offset:6144
	s_waitcnt lgkmcnt(3)
	s_setprio 1
	v_mfma_f32_32x32x16_bf16 v[114:129], v[142:145], v[146:149], v[114:129]
	v_mfma_f32_32x32x16_bf16 v[98:113], v[142:145], v[150:153], v[98:113]
	s_waitcnt lgkmcnt(2)
	v_mfma_f32_32x32x16_bf16 v[82:97], v[154:157], v[146:149], v[82:97]
	v_mfma_f32_32x32x16_bf16 v[66:81], v[154:157], v[150:153], v[66:81]
	s_waitcnt lgkmcnt(1)
	v_mfma_f32_32x32x16_bf16 v[50:65], v[158:161], v[146:149], v[50:65]
	v_mfma_f32_32x32x16_bf16 v[34:49], v[158:161], v[150:153], v[34:49]
	s_waitcnt lgkmcnt(0)
	v_mfma_f32_32x32x16_bf16 v[18:33], v[162:165], v[146:149], v[18:33]
	v_mfma_f32_32x32x16_bf16 v[2:17], v[162:165], v[150:153], v[2:17]
	s_setprio 0
	s_cmp_gt_i32 s4, 3
	s_cselect_b64 s[30:31], -1, 0
	s_add_i32 s2, s4, -8
	s_cmp_gt_u32 s2, 5
	s_cselect_b64 s[98:99], -1, 0
	s_and_b32 s2, s4, 0x7ffffffc
	s_cmp_lg_u32 s2, 20
	v_add_u32_e32 v238, s5, v225
	s_cselect_b64 s[2:3], -1, 0
	s_and_b32 s5, s4, 0x7ffffffe
	s_cmp_eq_u32 s5, 6
	s_cselect_b64 s[82:83], -1, 0
	s_sub_i32 s5, s4, 17
	v_add_u32_e32 v239, 0x800, v230
	v_add_u32_e32 v240, 0x1000, v230
	v_add_u32_e32 v241, 0x1800, v230
	s_waitcnt vmcnt(0) lgkmcnt(0)
	s_barrier
	s_mov_b32 s8, 0x0701c030
	s_mov_b32 s34, 0x380e00c0
	s_lshr_b32 s8, s8, s4
	s_lshr_b32 s34, s34, s4
	s_and_b32 s8, s8, 1
	s_and_b32 s34, s34, 1
	s_or_b32 s7, s8, s34
	s_cmp_eq_u32 s7, 0
	s_cbranch_scc1 .Lmy_g0e_std
	v_and_b32_e32 v151, 63, v200
	v_lshrrev_b32_e32 v150, 5, v151
	v_and_b32_e32 v146, 31, v151
	v_lshrrev_b32_e32 v147, 6, v200
	v_lshrrev_b32_e32 v152, 1, v147
	v_and_b32_e32 v148, 1, v147
	v_mul_u32_u24_e32 v147, 0x2200, v147
	v_lshlrev_b32_e32 v146, 2, v146
	s_movk_i32 s6, 0x440
	v_mad_u32_u24 v146, v150, s6, v146
	v_add_u32_e32 v146, v146, v147
	v_lshrrev_b32_e32 v150, 3, v151
	v_and_b32_e32 v149, 7, v151
	s_movk_i32 s6, 0x110
	v_mad_u32_u24 v147, v150, s6, v147
	v_lshl_add_u32 v147, v149, 5, v147
	v_lshl_add_u32 v152, v152, 7, s32
	v_add_u32_e32 v152, v152, v150
	s_lshl_b32 s6, s4, 7
	v_lshl_add_u32 v148, v148, 6, s6
	v_lshl_add_u32 v148, v149, 3, v148
	v_lshlrev_b32_e32 v148, 1, v148
	v_mul_u32_u24_e32 v152, 0x1e00, v152
	v_add_u32_e32 v148, v148, v152
	s_mov_b64 s[8:9], s[64:65]
	s_cmp_eq_u32 s34, 1
	s_cbranch_scc1 .Lmy_g0e_gate
	ds_write2_b32 v146, v114, v98 offset0:0 offset1:32
	ds_write2_b32 v146, v115, v99 offset0:68 offset1:100
	ds_write2_b32 v146, v116, v100 offset0:136 offset1:168
	ds_write2_b32 v146, v117, v101 offset0:204 offset1:236
	v_add_u32_e32 v146, 0x880, v146
	ds_write2_b32 v146, v118, v102 offset0:0 offset1:32
	ds_write2_b32 v146, v119, v103 offset0:68 offset1:100
	ds_write2_b32 v146, v120, v104 offset0:136 offset1:168
	ds_write2_b32 v146, v121, v105 offset0:204 offset1:236
	v_add_u32_e32 v146, 0x880, v146
	ds_write2_b32 v146, v122, v106 offset0:0 offset1:32
	ds_write2_b32 v146, v123, v107 offset0:68 offset1:100
	ds_write2_b32 v146, v124, v108 offset0:136 offset1:168
	ds_write2_b32 v146, v125, v109 offset0:204 offset1:236
	v_add_u32_e32 v146, 0x880, v146
	ds_write2_b32 v146, v126, v110 offset0:0 offset1:32
	ds_write2_b32 v146, v127, v111 offset0:68 offset1:100
	ds_write2_b32 v146, v128, v112 offset0:136 offset1:168
	ds_write2_b32 v146, v129, v113 offset0:204 offset1:236
	v_subrev_u32_e32 v146, 0x1980, v146
	s_waitcnt lgkmcnt(0)
	ds_read_b128 v[98:101], v147
	ds_read_b128 v[102:105], v147 offset:16
	ds_read_b128 v[106:109], v147 offset:2176
	ds_read_b128 v[110:113], v147 offset:2192
	ds_read_b128 v[114:117], v147 offset:4352
	ds_read_b128 v[118:121], v147 offset:4368
	ds_read_b128 v[122:125], v147 offset:6528
	ds_read_b128 v[126:129], v147 offset:6544
	s_waitcnt lgkmcnt(6)
	v_cvt_pk_bf16_f32 v154, v98, v99
	v_cvt_pk_bf16_f32 v155, v100, v101
	v_cvt_pk_bf16_f32 v156, v102, v103
	v_cvt_pk_bf16_f32 v157, v104, v105
	global_store_dwordx4 v148, v[154:157], s[8:9]
	s_add_u32 s8, s8, 0xf000
	s_addc_u32 s9, s9, 0
	s_waitcnt lgkmcnt(4)
	v_cvt_pk_bf16_f32 v158, v106, v107
	v_cvt_pk_bf16_f32 v159, v108, v109
	v_cvt_pk_bf16_f32 v160, v110, v111
	v_cvt_pk_bf16_f32 v161, v112, v113
	global_store_dwordx4 v148, v[158:161], s[8:9]
	s_add_u32 s8, s8, 0xf000
	s_addc_u32 s9, s9, 0
	s_waitcnt lgkmcnt(2)
	v_cvt_pk_bf16_f32 v162, v114, v115
	v_cvt_pk_bf16_f32 v163, v116, v117
	v_cvt_pk_bf16_f32 v164, v118, v119
	v_cvt_pk_bf16_f32 v165, v120, v121
	global_store_dwordx4 v148, v[162:165], s[8:9]
	s_add_u32 s8, s8, 0xf000
	s_addc_u32 s9, s9, 0
	s_waitcnt lgkmcnt(0)
	v_cvt_pk_bf16_f32 v166, v122, v123
	v_cvt_pk_bf16_f32 v167, v124, v125
	v_cvt_pk_bf16_f32 v168, v126, v127
	v_cvt_pk_bf16_f32 v169, v128, v129
	global_store_dwordx4 v148, v[166:169], s[8:9]
	s_add_u32 s8, s8, 0xf000
	s_addc_u32 s9, s9, 0
	ds_write2_b32 v146, v82, v66 offset0:0 offset1:32
	ds_write2_b32 v146, v83, v67 offset0:68 offset1:100
	ds_write2_b32 v146, v84, v68 offset0:136 offset1:168
	ds_write2_b32 v146, v85, v69 offset0:204 offset1:236
	v_add_u32_e32 v146, 0x880, v146
	ds_write2_b32 v146, v86, v70 offset0:0 offset1:32
	ds_write2_b32 v146, v87, v71 offset0:68 offset1:100
	ds_write2_b32 v146, v88, v72 offset0:136 offset1:168
	ds_write2_b32 v146, v89, v73 offset0:204 offset1:236
	v_add_u32_e32 v146, 0x880, v146
	ds_write2_b32 v146, v90, v74 offset0:0 offset1:32
	ds_write2_b32 v146, v91, v75 offset0:68 offset1:100
	ds_write2_b32 v146, v92, v76 offset0:136 offset1:168
	ds_write2_b32 v146, v93, v77 offset0:204 offset1:236
	v_add_u32_e32 v146, 0x880, v146
	ds_write2_b32 v146, v94, v78 offset0:0 offset1:32
	ds_write2_b32 v146, v95, v79 offset0:68 offset1:100
	ds_write2_b32 v146, v96, v80 offset0:136 offset1:168
	ds_write2_b32 v146, v97, v81 offset0:204 offset1:236
	v_subrev_u32_e32 v146, 0x1980, v146
	s_waitcnt lgkmcnt(0)
	ds_read_b128 v[66:69], v147
	ds_read_b128 v[70:73], v147 offset:16
	ds_read_b128 v[74:77], v147 offset:2176
	ds_read_b128 v[78:81], v147 offset:2192
	ds_read_b128 v[82:85], v147 offset:4352
	ds_read_b128 v[86:89], v147 offset:4368
	ds_read_b128 v[90:93], v147 offset:6528
	ds_read_b128 v[94:97], v147 offset:6544
	s_waitcnt lgkmcnt(6)
	v_cvt_pk_bf16_f32 v154, v66, v67
	v_cvt_pk_bf16_f32 v155, v68, v69
	v_cvt_pk_bf16_f32 v156, v70, v71
	v_cvt_pk_bf16_f32 v157, v72, v73
	global_store_dwordx4 v148, v[154:157], s[8:9]
	s_add_u32 s8, s8, 0xf000
	s_addc_u32 s9, s9, 0
	s_waitcnt lgkmcnt(4)
	v_cvt_pk_bf16_f32 v158, v74, v75
	v_cvt_pk_bf16_f32 v159, v76, v77
	v_cvt_pk_bf16_f32 v160, v78, v79
	v_cvt_pk_bf16_f32 v161, v80, v81
	global_store_dwordx4 v148, v[158:161], s[8:9]
	s_add_u32 s8, s8, 0xf000
	s_addc_u32 s9, s9, 0
	s_waitcnt lgkmcnt(2)
	v_cvt_pk_bf16_f32 v162, v82, v83
	v_cvt_pk_bf16_f32 v163, v84, v85
	v_cvt_pk_bf16_f32 v164, v86, v87
	v_cvt_pk_bf16_f32 v165, v88, v89
	global_store_dwordx4 v148, v[162:165], s[8:9]
	s_add_u32 s8, s8, 0xf000
	s_addc_u32 s9, s9, 0
	s_waitcnt lgkmcnt(0)
	v_cvt_pk_bf16_f32 v166, v90, v91
	v_cvt_pk_bf16_f32 v167, v92, v93
	v_cvt_pk_bf16_f32 v168, v94, v95
	v_cvt_pk_bf16_f32 v169, v96, v97
	global_store_dwordx4 v148, v[166:169], s[8:9]
	s_add_u32 s8, s8, 0xf000
	s_addc_u32 s9, s9, 0
	ds_write2_b32 v146, v50, v34 offset0:0 offset1:32
	ds_write2_b32 v146, v51, v35 offset0:68 offset1:100
	ds_write2_b32 v146, v52, v36 offset0:136 offset1:168
	ds_write2_b32 v146, v53, v37 offset0:204 offset1:236
	v_add_u32_e32 v146, 0x880, v146
	ds_write2_b32 v146, v54, v38 offset0:0 offset1:32
	ds_write2_b32 v146, v55, v39 offset0:68 offset1:100
	ds_write2_b32 v146, v56, v40 offset0:136 offset1:168
	ds_write2_b32 v146, v57, v41 offset0:204 offset1:236
	v_add_u32_e32 v146, 0x880, v146
	ds_write2_b32 v146, v58, v42 offset0:0 offset1:32
	ds_write2_b32 v146, v59, v43 offset0:68 offset1:100
	ds_write2_b32 v146, v60, v44 offset0:136 offset1:168
	ds_write2_b32 v146, v61, v45 offset0:204 offset1:236
	v_add_u32_e32 v146, 0x880, v146
	ds_write2_b32 v146, v62, v46 offset0:0 offset1:32
	ds_write2_b32 v146, v63, v47 offset0:68 offset1:100
	ds_write2_b32 v146, v64, v48 offset0:136 offset1:168
	ds_write2_b32 v146, v65, v49 offset0:204 offset1:236
	v_subrev_u32_e32 v146, 0x1980, v146
	s_waitcnt lgkmcnt(0)
	ds_read_b128 v[34:37], v147
	ds_read_b128 v[38:41], v147 offset:16
	ds_read_b128 v[42:45], v147 offset:2176
	ds_read_b128 v[46:49], v147 offset:2192
	ds_read_b128 v[50:53], v147 offset:4352
	ds_read_b128 v[54:57], v147 offset:4368
	ds_read_b128 v[58:61], v147 offset:6528
	ds_read_b128 v[62:65], v147 offset:6544
	s_waitcnt lgkmcnt(6)
	v_cvt_pk_bf16_f32 v154, v34, v35
	v_cvt_pk_bf16_f32 v155, v36, v37
	v_cvt_pk_bf16_f32 v156, v38, v39
	v_cvt_pk_bf16_f32 v157, v40, v41
	global_store_dwordx4 v148, v[154:157], s[8:9]
	s_add_u32 s8, s8, 0xf000
	s_addc_u32 s9, s9, 0
	s_waitcnt lgkmcnt(4)
	v_cvt_pk_bf16_f32 v158, v42, v43
	v_cvt_pk_bf16_f32 v159, v44, v45
	v_cvt_pk_bf16_f32 v160, v46, v47
	v_cvt_pk_bf16_f32 v161, v48, v49
	global_store_dwordx4 v148, v[158:161], s[8:9]
	s_add_u32 s8, s8, 0xf000
	s_addc_u32 s9, s9, 0
	s_waitcnt lgkmcnt(2)
	v_cvt_pk_bf16_f32 v162, v50, v51
	v_cvt_pk_bf16_f32 v163, v52, v53
	v_cvt_pk_bf16_f32 v164, v54, v55
	v_cvt_pk_bf16_f32 v165, v56, v57
	global_store_dwordx4 v148, v[162:165], s[8:9]
	s_add_u32 s8, s8, 0xf000
	s_addc_u32 s9, s9, 0
	s_waitcnt lgkmcnt(0)
	v_cvt_pk_bf16_f32 v166, v58, v59
	v_cvt_pk_bf16_f32 v167, v60, v61
	v_cvt_pk_bf16_f32 v168, v62, v63
	v_cvt_pk_bf16_f32 v169, v64, v65
	global_store_dwordx4 v148, v[166:169], s[8:9]
	s_add_u32 s8, s8, 0xf000
	s_addc_u32 s9, s9, 0
	ds_write2_b32 v146, v18, v2 offset0:0 offset1:32
	ds_write2_b32 v146, v19, v3 offset0:68 offset1:100
	ds_write2_b32 v146, v20, v4 offset0:136 offset1:168
	ds_write2_b32 v146, v21, v5 offset0:204 offset1:236
	v_add_u32_e32 v146, 0x880, v146
	ds_write2_b32 v146, v22, v6 offset0:0 offset1:32
	ds_write2_b32 v146, v23, v7 offset0:68 offset1:100
	ds_write2_b32 v146, v24, v8 offset0:136 offset1:168
	ds_write2_b32 v146, v25, v9 offset0:204 offset1:236
	v_add_u32_e32 v146, 0x880, v146
	ds_write2_b32 v146, v26, v10 offset0:0 offset1:32
	ds_write2_b32 v146, v27, v11 offset0:68 offset1:100
	ds_write2_b32 v146, v28, v12 offset0:136 offset1:168
	ds_write2_b32 v146, v29, v13 offset0:204 offset1:236
	v_add_u32_e32 v146, 0x880, v146
	ds_write2_b32 v146, v30, v14 offset0:0 offset1:32
	ds_write2_b32 v146, v31, v15 offset0:68 offset1:100
	ds_write2_b32 v146, v32, v16 offset0:136 offset1:168
	ds_write2_b32 v146, v33, v17 offset0:204 offset1:236
	v_subrev_u32_e32 v146, 0x1980, v146
	s_waitcnt lgkmcnt(0)
	ds_read_b128 v[2:5], v147
	ds_read_b128 v[6:9], v147 offset:16
	ds_read_b128 v[10:13], v147 offset:2176
	ds_read_b128 v[14:17], v147 offset:2192
	ds_read_b128 v[18:21], v147 offset:4352
	ds_read_b128 v[22:25], v147 offset:4368
	ds_read_b128 v[26:29], v147 offset:6528
	ds_read_b128 v[30:33], v147 offset:6544
	s_waitcnt lgkmcnt(6)
	v_cvt_pk_bf16_f32 v154, v2, v3
	v_cvt_pk_bf16_f32 v155, v4, v5
	v_cvt_pk_bf16_f32 v156, v6, v7
	v_cvt_pk_bf16_f32 v157, v8, v9
	global_store_dwordx4 v148, v[154:157], s[8:9]
	s_add_u32 s8, s8, 0xf000
	s_addc_u32 s9, s9, 0
	s_waitcnt lgkmcnt(4)
	v_cvt_pk_bf16_f32 v158, v10, v11
	v_cvt_pk_bf16_f32 v159, v12, v13
	v_cvt_pk_bf16_f32 v160, v14, v15
	v_cvt_pk_bf16_f32 v161, v16, v17
	global_store_dwordx4 v148, v[158:161], s[8:9]
	s_add_u32 s8, s8, 0xf000
	s_addc_u32 s9, s9, 0
	s_waitcnt lgkmcnt(2)
	v_cvt_pk_bf16_f32 v162, v18, v19
	v_cvt_pk_bf16_f32 v163, v20, v21
	v_cvt_pk_bf16_f32 v164, v22, v23
	v_cvt_pk_bf16_f32 v165, v24, v25
	global_store_dwordx4 v148, v[162:165], s[8:9]
	s_add_u32 s8, s8, 0xf000
	s_addc_u32 s9, s9, 0
	s_waitcnt lgkmcnt(0)
	v_cvt_pk_bf16_f32 v166, v26, v27
	v_cvt_pk_bf16_f32 v167, v28, v29
	v_cvt_pk_bf16_f32 v168, v30, v31
	v_cvt_pk_bf16_f32 v169, v32, v33
	global_store_dwordx4 v148, v[166:169], s[8:9]
	s_add_u32 s8, s8, 0xf000
	s_addc_u32 s9, s9, 0
	s_add_i32 s70, s70, s10
	s_cmp_lt_i32 s70, s71
	s_waitcnt lgkmcnt(0)
	s_barrier
	s_cbranch_scc0 .LBB0_209
	s_branch .LBB0_215
.Lmy_g0e_gate:
	ds_write2_b32 v146, v114, v98 offset0:0 offset1:32
	ds_write2_b32 v146, v115, v99 offset0:68 offset1:100
	ds_write2_b32 v146, v116, v100 offset0:136 offset1:168
	ds_write2_b32 v146, v117, v101 offset0:204 offset1:236
	v_add_u32_e32 v146, 0x880, v146
	ds_write2_b32 v146, v118, v102 offset0:0 offset1:32
	ds_write2_b32 v146, v119, v103 offset0:68 offset1:100
	ds_write2_b32 v146, v120, v104 offset0:136 offset1:168
	ds_write2_b32 v146, v121, v105 offset0:204 offset1:236
	v_add_u32_e32 v146, 0x880, v146
	ds_write2_b32 v146, v122, v106 offset0:0 offset1:32
	ds_write2_b32 v146, v123, v107 offset0:68 offset1:100
	ds_write2_b32 v146, v124, v108 offset0:136 offset1:168
	ds_write2_b32 v146, v125, v109 offset0:204 offset1:236
	v_add_u32_e32 v146, 0x880, v146
	ds_write2_b32 v146, v126, v110 offset0:0 offset1:32
	ds_write2_b32 v146, v127, v111 offset0:68 offset1:100
	ds_write2_b32 v146, v128, v112 offset0:136 offset1:168
	ds_write2_b32 v146, v129, v113 offset0:204 offset1:236
	v_subrev_u32_e32 v146, 0x1980, v146
	s_waitcnt lgkmcnt(0)
	ds_read_b128 v[98:101], v147
	ds_read_b128 v[102:105], v147 offset:16
	ds_read_b128 v[106:109], v147 offset:2176
	ds_read_b128 v[110:113], v147 offset:2192
	ds_read_b128 v[114:117], v147 offset:4352
	ds_read_b128 v[118:121], v147 offset:4368
	ds_read_b128 v[122:125], v147 offset:6528
	ds_read_b128 v[126:129], v147 offset:6544
	s_waitcnt lgkmcnt(6)
	v_mul_f32_e32 v170, 0xbfb8aa3b, v98
	v_mul_f32_e32 v171, 0xbfb8aa3b, v99
	v_mul_f32_e32 v172, 0xbfb8aa3b, v100
	v_mul_f32_e32 v173, 0xbfb8aa3b, v101
	v_exp_f32_e32 v170, v170
	v_exp_f32_e32 v171, v171
	v_exp_f32_e32 v172, v172
	v_exp_f32_e32 v173, v173
	v_add_f32_e32 v170, 1.0, v170
	v_add_f32_e32 v171, 1.0, v171
	v_add_f32_e32 v172, 1.0, v172
	v_add_f32_e32 v173, 1.0, v173
	v_rcp_f32_e32 v170, v170
	v_rcp_f32_e32 v171, v171
	v_rcp_f32_e32 v172, v172
	v_rcp_f32_e32 v173, v173
	s_nop 0
	v_mul_f32_e32 v98, v98, v170
	v_mul_f32_e32 v99, v99, v171
	v_mul_f32_e32 v100, v100, v172
	v_mul_f32_e32 v101, v101, v173
	v_cvt_pk_bf16_f32 v154, v98, v99
	v_cvt_pk_bf16_f32 v155, v100, v101
	v_mul_f32_e32 v170, 0xbfb8aa3b, v102
	v_mul_f32_e32 v171, 0xbfb8aa3b, v103
	v_mul_f32_e32 v172, 0xbfb8aa3b, v104
	v_mul_f32_e32 v173, 0xbfb8aa3b, v105
	v_exp_f32_e32 v170, v170
	v_exp_f32_e32 v171, v171
	v_exp_f32_e32 v172, v172
	v_exp_f32_e32 v173, v173
	v_add_f32_e32 v170, 1.0, v170
	v_add_f32_e32 v171, 1.0, v171
	v_add_f32_e32 v172, 1.0, v172
	v_add_f32_e32 v173, 1.0, v173
	v_rcp_f32_e32 v170, v170
	v_rcp_f32_e32 v171, v171
	v_rcp_f32_e32 v172, v172
	v_rcp_f32_e32 v173, v173
	s_nop 0
	v_mul_f32_e32 v102, v102, v170
	v_mul_f32_e32 v103, v103, v171
	v_mul_f32_e32 v104, v104, v172
	v_mul_f32_e32 v105, v105, v173
	v_cvt_pk_bf16_f32 v156, v102, v103
	v_cvt_pk_bf16_f32 v157, v104, v105
	global_store_dwordx4 v148, v[154:157], s[8:9]
	s_add_u32 s8, s8, 0xf000
	s_addc_u32 s9, s9, 0
	s_waitcnt lgkmcnt(4)
	v_mul_f32_e32 v170, 0xbfb8aa3b, v106
	v_mul_f32_e32 v171, 0xbfb8aa3b, v107
	v_mul_f32_e32 v172, 0xbfb8aa3b, v108
	v_mul_f32_e32 v173, 0xbfb8aa3b, v109
	v_exp_f32_e32 v170, v170
	v_exp_f32_e32 v171, v171
	v_exp_f32_e32 v172, v172
	v_exp_f32_e32 v173, v173
	v_add_f32_e32 v170, 1.0, v170
	v_add_f32_e32 v171, 1.0, v171
	v_add_f32_e32 v172, 1.0, v172
	v_add_f32_e32 v173, 1.0, v173
	v_rcp_f32_e32 v170, v170
	v_rcp_f32_e32 v171, v171
	v_rcp_f32_e32 v172, v172
	v_rcp_f32_e32 v173, v173
	s_nop 0
	v_mul_f32_e32 v106, v106, v170
	v_mul_f32_e32 v107, v107, v171
	v_mul_f32_e32 v108, v108, v172
	v_mul_f32_e32 v109, v109, v173
	v_cvt_pk_bf16_f32 v158, v106, v107
	v_cvt_pk_bf16_f32 v159, v108, v109
	v_mul_f32_e32 v170, 0xbfb8aa3b, v110
	v_mul_f32_e32 v171, 0xbfb8aa3b, v111
	v_mul_f32_e32 v172, 0xbfb8aa3b, v112
	v_mul_f32_e32 v173, 0xbfb8aa3b, v113
	v_exp_f32_e32 v170, v170
	v_exp_f32_e32 v171, v171
	v_exp_f32_e32 v172, v172
	v_exp_f32_e32 v173, v173
	v_add_f32_e32 v170, 1.0, v170
	v_add_f32_e32 v171, 1.0, v171
	v_add_f32_e32 v172, 1.0, v172
	v_add_f32_e32 v173, 1.0, v173
	v_rcp_f32_e32 v170, v170
	v_rcp_f32_e32 v171, v171
	v_rcp_f32_e32 v172, v172
	v_rcp_f32_e32 v173, v173
	s_nop 0
	v_mul_f32_e32 v110, v110, v170
	v_mul_f32_e32 v111, v111, v171
	v_mul_f32_e32 v112, v112, v172
	v_mul_f32_e32 v113, v113, v173
	v_cvt_pk_bf16_f32 v160, v110, v111
	v_cvt_pk_bf16_f32 v161, v112, v113
	global_store_dwordx4 v148, v[158:161], s[8:9]
	s_add_u32 s8, s8, 0xf000
	s_addc_u32 s9, s9, 0
	s_waitcnt lgkmcnt(2)
	v_mul_f32_e32 v170, 0xbfb8aa3b, v114
	v_mul_f32_e32 v171, 0xbfb8aa3b, v115
	v_mul_f32_e32 v172, 0xbfb8aa3b, v116
	v_mul_f32_e32 v173, 0xbfb8aa3b, v117
	v_exp_f32_e32 v170, v170
	v_exp_f32_e32 v171, v171
	v_exp_f32_e32 v172, v172
	v_exp_f32_e32 v173, v173
	v_add_f32_e32 v170, 1.0, v170
	v_add_f32_e32 v171, 1.0, v171
	v_add_f32_e32 v172, 1.0, v172
	v_add_f32_e32 v173, 1.0, v173
	v_rcp_f32_e32 v170, v170
	v_rcp_f32_e32 v171, v171
	v_rcp_f32_e32 v172, v172
	v_rcp_f32_e32 v173, v173
	s_nop 0
	v_mul_f32_e32 v114, v114, v170
	v_mul_f32_e32 v115, v115, v171
	v_mul_f32_e32 v116, v116, v172
	v_mul_f32_e32 v117, v117, v173
	v_cvt_pk_bf16_f32 v162, v114, v115
	v_cvt_pk_bf16_f32 v163, v116, v117
	v_mul_f32_e32 v170, 0xbfb8aa3b, v118
	v_mul_f32_e32 v171, 0xbfb8aa3b, v119
	v_mul_f32_e32 v172, 0xbfb8aa3b, v120
	v_mul_f32_e32 v173, 0xbfb8aa3b, v121
	v_exp_f32_e32 v170, v170
	v_exp_f32_e32 v171, v171
	v_exp_f32_e32 v172, v172
	v_exp_f32_e32 v173, v173
	v_add_f32_e32 v170, 1.0, v170
	v_add_f32_e32 v171, 1.0, v171
	v_add_f32_e32 v172, 1.0, v172
	v_add_f32_e32 v173, 1.0, v173
	v_rcp_f32_e32 v170, v170
	v_rcp_f32_e32 v171, v171
	v_rcp_f32_e32 v172, v172
	v_rcp_f32_e32 v173, v173
	s_nop 0
	v_mul_f32_e32 v118, v118, v170
	v_mul_f32_e32 v119, v119, v171
	v_mul_f32_e32 v120, v120, v172
	v_mul_f32_e32 v121, v121, v173
	v_cvt_pk_bf16_f32 v164, v118, v119
	v_cvt_pk_bf16_f32 v165, v120, v121
	global_store_dwordx4 v148, v[162:165], s[8:9]
	s_add_u32 s8, s8, 0xf000
	s_addc_u32 s9, s9, 0
	s_waitcnt lgkmcnt(0)
	v_mul_f32_e32 v170, 0xbfb8aa3b, v122
	v_mul_f32_e32 v171, 0xbfb8aa3b, v123
	v_mul_f32_e32 v172, 0xbfb8aa3b, v124
	v_mul_f32_e32 v173, 0xbfb8aa3b, v125
	v_exp_f32_e32 v170, v170
	v_exp_f32_e32 v171, v171
	v_exp_f32_e32 v172, v172
	v_exp_f32_e32 v173, v173
	v_add_f32_e32 v170, 1.0, v170
	v_add_f32_e32 v171, 1.0, v171
	v_add_f32_e32 v172, 1.0, v172
	v_add_f32_e32 v173, 1.0, v173
	v_rcp_f32_e32 v170, v170
	v_rcp_f32_e32 v171, v171
	v_rcp_f32_e32 v172, v172
	v_rcp_f32_e32 v173, v173
	s_nop 0
	v_mul_f32_e32 v122, v122, v170
	v_mul_f32_e32 v123, v123, v171
	v_mul_f32_e32 v124, v124, v172
	v_mul_f32_e32 v125, v125, v173
	v_cvt_pk_bf16_f32 v166, v122, v123
	v_cvt_pk_bf16_f32 v167, v124, v125
	v_mul_f32_e32 v170, 0xbfb8aa3b, v126
	v_mul_f32_e32 v171, 0xbfb8aa3b, v127
	v_mul_f32_e32 v172, 0xbfb8aa3b, v128
	v_mul_f32_e32 v173, 0xbfb8aa3b, v129
	v_exp_f32_e32 v170, v170
	v_exp_f32_e32 v171, v171
	v_exp_f32_e32 v172, v172
	v_exp_f32_e32 v173, v173
	v_add_f32_e32 v170, 1.0, v170
	v_add_f32_e32 v171, 1.0, v171
	v_add_f32_e32 v172, 1.0, v172
	v_add_f32_e32 v173, 1.0, v173
	v_rcp_f32_e32 v170, v170
	v_rcp_f32_e32 v171, v171
	v_rcp_f32_e32 v172, v172
	v_rcp_f32_e32 v173, v173
	s_nop 0
	v_mul_f32_e32 v126, v126, v170
	v_mul_f32_e32 v127, v127, v171
	v_mul_f32_e32 v128, v128, v172
	v_mul_f32_e32 v129, v129, v173
	v_cvt_pk_bf16_f32 v168, v126, v127
	v_cvt_pk_bf16_f32 v169, v128, v129
	global_store_dwordx4 v148, v[166:169], s[8:9]
	s_add_u32 s8, s8, 0xf000
	s_addc_u32 s9, s9, 0
	ds_write2_b32 v146, v82, v66 offset0:0 offset1:32
	ds_write2_b32 v146, v83, v67 offset0:68 offset1:100
	ds_write2_b32 v146, v84, v68 offset0:136 offset1:168
	ds_write2_b32 v146, v85, v69 offset0:204 offset1:236
	v_add_u32_e32 v146, 0x880, v146
	ds_write2_b32 v146, v86, v70 offset0:0 offset1:32
	ds_write2_b32 v146, v87, v71 offset0:68 offset1:100
	ds_write2_b32 v146, v88, v72 offset0:136 offset1:168
	ds_write2_b32 v146, v89, v73 offset0:204 offset1:236
	v_add_u32_e32 v146, 0x880, v146
	ds_write2_b32 v146, v90, v74 offset0:0 offset1:32
	ds_write2_b32 v146, v91, v75 offset0:68 offset1:100
	ds_write2_b32 v146, v92, v76 offset0:136 offset1:168
	ds_write2_b32 v146, v93, v77 offset0:204 offset1:236
	v_add_u32_e32 v146, 0x880, v146
	ds_write2_b32 v146, v94, v78 offset0:0 offset1:32
	ds_write2_b32 v146, v95, v79 offset0:68 offset1:100
	ds_write2_b32 v146, v96, v80 offset0:136 offset1:168
	ds_write2_b32 v146, v97, v81 offset0:204 offset1:236
	v_subrev_u32_e32 v146, 0x1980, v146
	s_waitcnt lgkmcnt(0)
	ds_read_b128 v[66:69], v147
	ds_read_b128 v[70:73], v147 offset:16
	ds_read_b128 v[74:77], v147 offset:2176
	ds_read_b128 v[78:81], v147 offset:2192
	ds_read_b128 v[82:85], v147 offset:4352
	ds_read_b128 v[86:89], v147 offset:4368
	ds_read_b128 v[90:93], v147 offset:6528
	ds_read_b128 v[94:97], v147 offset:6544
	s_waitcnt lgkmcnt(6)
	v_mul_f32_e32 v170, 0xbfb8aa3b, v66
	v_mul_f32_e32 v171, 0xbfb8aa3b, v67
	v_mul_f32_e32 v172, 0xbfb8aa3b, v68
	v_mul_f32_e32 v173, 0xbfb8aa3b, v69
	v_exp_f32_e32 v170, v170
	v_exp_f32_e32 v171, v171
	v_exp_f32_e32 v172, v172
	v_exp_f32_e32 v173, v173
	v_add_f32_e32 v170, 1.0, v170
	v_add_f32_e32 v171, 1.0, v171
	v_add_f32_e32 v172, 1.0, v172
	v_add_f32_e32 v173, 1.0, v173
	v_rcp_f32_e32 v170, v170
	v_rcp_f32_e32 v171, v171
	v_rcp_f32_e32 v172, v172
	v_rcp_f32_e32 v173, v173
	s_nop 0
	v_mul_f32_e32 v66, v66, v170
	v_mul_f32_e32 v67, v67, v171
	v_mul_f32_e32 v68, v68, v172
	v_mul_f32_e32 v69, v69, v173
	v_cvt_pk_bf16_f32 v154, v66, v67
	v_cvt_pk_bf16_f32 v155, v68, v69
	v_mul_f32_e32 v170, 0xbfb8aa3b, v70
	v_mul_f32_e32 v171, 0xbfb8aa3b, v71
	v_mul_f32_e32 v172, 0xbfb8aa3b, v72
	v_mul_f32_e32 v173, 0xbfb8aa3b, v73
	v_exp_f32_e32 v170, v170
	v_exp_f32_e32 v171, v171
	v_exp_f32_e32 v172, v172
	v_exp_f32_e32 v173, v173
	v_add_f32_e32 v170, 1.0, v170
	v_add_f32_e32 v171, 1.0, v171
	v_add_f32_e32 v172, 1.0, v172
	v_add_f32_e32 v173, 1.0, v173
	v_rcp_f32_e32 v170, v170
	v_rcp_f32_e32 v171, v171
	v_rcp_f32_e32 v172, v172
	v_rcp_f32_e32 v173, v173
	s_nop 0
	v_mul_f32_e32 v70, v70, v170
	v_mul_f32_e32 v71, v71, v171
	v_mul_f32_e32 v72, v72, v172
	v_mul_f32_e32 v73, v73, v173
	v_cvt_pk_bf16_f32 v156, v70, v71
	v_cvt_pk_bf16_f32 v157, v72, v73
	global_store_dwordx4 v148, v[154:157], s[8:9]
	s_add_u32 s8, s8, 0xf000
	s_addc_u32 s9, s9, 0
	s_waitcnt lgkmcnt(4)
	v_mul_f32_e32 v170, 0xbfb8aa3b, v74
	v_mul_f32_e32 v171, 0xbfb8aa3b, v75
	v_mul_f32_e32 v172, 0xbfb8aa3b, v76
	v_mul_f32_e32 v173, 0xbfb8aa3b, v77
	v_exp_f32_e32 v170, v170
	v_exp_f32_e32 v171, v171
	v_exp_f32_e32 v172, v172
	v_exp_f32_e32 v173, v173
	v_add_f32_e32 v170, 1.0, v170
	v_add_f32_e32 v171, 1.0, v171
	v_add_f32_e32 v172, 1.0, v172
	v_add_f32_e32 v173, 1.0, v173
	v_rcp_f32_e32 v170, v170
	v_rcp_f32_e32 v171, v171
	v_rcp_f32_e32 v172, v172
	v_rcp_f32_e32 v173, v173
	s_nop 0
	v_mul_f32_e32 v74, v74, v170
	v_mul_f32_e32 v75, v75, v171
	v_mul_f32_e32 v76, v76, v172
	v_mul_f32_e32 v77, v77, v173
	v_cvt_pk_bf16_f32 v158, v74, v75
	v_cvt_pk_bf16_f32 v159, v76, v77
	v_mul_f32_e32 v170, 0xbfb8aa3b, v78
	v_mul_f32_e32 v171, 0xbfb8aa3b, v79
	v_mul_f32_e32 v172, 0xbfb8aa3b, v80
	v_mul_f32_e32 v173, 0xbfb8aa3b, v81
	v_exp_f32_e32 v170, v170
	v_exp_f32_e32 v171, v171
	v_exp_f32_e32 v172, v172
	v_exp_f32_e32 v173, v173
	v_add_f32_e32 v170, 1.0, v170
	v_add_f32_e32 v171, 1.0, v171
	v_add_f32_e32 v172, 1.0, v172
	v_add_f32_e32 v173, 1.0, v173
	v_rcp_f32_e32 v170, v170
	v_rcp_f32_e32 v171, v171
	v_rcp_f32_e32 v172, v172
	v_rcp_f32_e32 v173, v173
	s_nop 0
	v_mul_f32_e32 v78, v78, v170
	v_mul_f32_e32 v79, v79, v171
	v_mul_f32_e32 v80, v80, v172
	v_mul_f32_e32 v81, v81, v173
	v_cvt_pk_bf16_f32 v160, v78, v79
	v_cvt_pk_bf16_f32 v161, v80, v81
	global_store_dwordx4 v148, v[158:161], s[8:9]
	s_add_u32 s8, s8, 0xf000
	s_addc_u32 s9, s9, 0
	s_waitcnt lgkmcnt(2)
	v_mul_f32_e32 v170, 0xbfb8aa3b, v82
	v_mul_f32_e32 v171, 0xbfb8aa3b, v83
	v_mul_f32_e32 v172, 0xbfb8aa3b, v84
	v_mul_f32_e32 v173, 0xbfb8aa3b, v85
	v_exp_f32_e32 v170, v170
	v_exp_f32_e32 v171, v171
	v_exp_f32_e32 v172, v172
	v_exp_f32_e32 v173, v173
	v_add_f32_e32 v170, 1.0, v170
	v_add_f32_e32 v171, 1.0, v171
	v_add_f32_e32 v172, 1.0, v172
	v_add_f32_e32 v173, 1.0, v173
	v_rcp_f32_e32 v170, v170
	v_rcp_f32_e32 v171, v171
	v_rcp_f32_e32 v172, v172
	v_rcp_f32_e32 v173, v173
	s_nop 0
	v_mul_f32_e32 v82, v82, v170
	v_mul_f32_e32 v83, v83, v171
	v_mul_f32_e32 v84, v84, v172
	v_mul_f32_e32 v85, v85, v173
	v_cvt_pk_bf16_f32 v162, v82, v83
	v_cvt_pk_bf16_f32 v163, v84, v85
	v_mul_f32_e32 v170, 0xbfb8aa3b, v86
	v_mul_f32_e32 v171, 0xbfb8aa3b, v87
	v_mul_f32_e32 v172, 0xbfb8aa3b, v88
	v_mul_f32_e32 v173, 0xbfb8aa3b, v89
	v_exp_f32_e32 v170, v170
	v_exp_f32_e32 v171, v171
	v_exp_f32_e32 v172, v172
	v_exp_f32_e32 v173, v173
	v_add_f32_e32 v170, 1.0, v170
	v_add_f32_e32 v171, 1.0, v171
	v_add_f32_e32 v172, 1.0, v172
	v_add_f32_e32 v173, 1.0, v173
	v_rcp_f32_e32 v170, v170
	v_rcp_f32_e32 v171, v171
	v_rcp_f32_e32 v172, v172
	v_rcp_f32_e32 v173, v173
	s_nop 0
	v_mul_f32_e32 v86, v86, v170
	v_mul_f32_e32 v87, v87, v171
	v_mul_f32_e32 v88, v88, v172
	v_mul_f32_e32 v89, v89, v173
	v_cvt_pk_bf16_f32 v164, v86, v87
	v_cvt_pk_bf16_f32 v165, v88, v89
	global_store_dwordx4 v148, v[162:165], s[8:9]
	s_add_u32 s8, s8, 0xf000
	s_addc_u32 s9, s9, 0
	s_waitcnt lgkmcnt(0)
	v_mul_f32_e32 v170, 0xbfb8aa3b, v90
	v_mul_f32_e32 v171, 0xbfb8aa3b, v91
	v_mul_f32_e32 v172, 0xbfb8aa3b, v92
	v_mul_f32_e32 v173, 0xbfb8aa3b, v93
	v_exp_f32_e32 v170, v170
	v_exp_f32_e32 v171, v171
	v_exp_f32_e32 v172, v172
	v_exp_f32_e32 v173, v173
	v_add_f32_e32 v170, 1.0, v170
	v_add_f32_e32 v171, 1.0, v171
	v_add_f32_e32 v172, 1.0, v172
	v_add_f32_e32 v173, 1.0, v173
	v_rcp_f32_e32 v170, v170
	v_rcp_f32_e32 v171, v171
	v_rcp_f32_e32 v172, v172
	v_rcp_f32_e32 v173, v173
	s_nop 0
	v_mul_f32_e32 v90, v90, v170
	v_mul_f32_e32 v91, v91, v171
	v_mul_f32_e32 v92, v92, v172
	v_mul_f32_e32 v93, v93, v173
	v_cvt_pk_bf16_f32 v166, v90, v91
	v_cvt_pk_bf16_f32 v167, v92, v93
	v_mul_f32_e32 v170, 0xbfb8aa3b, v94
	v_mul_f32_e32 v171, 0xbfb8aa3b, v95
	v_mul_f32_e32 v172, 0xbfb8aa3b, v96
	v_mul_f32_e32 v173, 0xbfb8aa3b, v97
	v_exp_f32_e32 v170, v170
	v_exp_f32_e32 v171, v171
	v_exp_f32_e32 v172, v172
	v_exp_f32_e32 v173, v173
	v_add_f32_e32 v170, 1.0, v170
	v_add_f32_e32 v171, 1.0, v171
	v_add_f32_e32 v172, 1.0, v172
	v_add_f32_e32 v173, 1.0, v173
	v_rcp_f32_e32 v170, v170
	v_rcp_f32_e32 v171, v171
	v_rcp_f32_e32 v172, v172
	v_rcp_f32_e32 v173, v173
	s_nop 0
	v_mul_f32_e32 v94, v94, v170
	v_mul_f32_e32 v95, v95, v171
	v_mul_f32_e32 v96, v96, v172
	v_mul_f32_e32 v97, v97, v173
	v_cvt_pk_bf16_f32 v168, v94, v95
	v_cvt_pk_bf16_f32 v169, v96, v97
	global_store_dwordx4 v148, v[166:169], s[8:9]
	s_add_u32 s8, s8, 0xf000
	s_addc_u32 s9, s9, 0
	ds_write2_b32 v146, v50, v34 offset0:0 offset1:32
	ds_write2_b32 v146, v51, v35 offset0:68 offset1:100
	ds_write2_b32 v146, v52, v36 offset0:136 offset1:168
	ds_write2_b32 v146, v53, v37 offset0:204 offset1:236
	v_add_u32_e32 v146, 0x880, v146
	ds_write2_b32 v146, v54, v38 offset0:0 offset1:32
	ds_write2_b32 v146, v55, v39 offset0:68 offset1:100
	ds_write2_b32 v146, v56, v40 offset0:136 offset1:168
	ds_write2_b32 v146, v57, v41 offset0:204 offset1:236
	v_add_u32_e32 v146, 0x880, v146
	ds_write2_b32 v146, v58, v42 offset0:0 offset1:32
	ds_write2_b32 v146, v59, v43 offset0:68 offset1:100
	ds_write2_b32 v146, v60, v44 offset0:136 offset1:168
	ds_write2_b32 v146, v61, v45 offset0:204 offset1:236
	v_add_u32_e32 v146, 0x880, v146
	ds_write2_b32 v146, v62, v46 offset0:0 offset1:32
	ds_write2_b32 v146, v63, v47 offset0:68 offset1:100
	ds_write2_b32 v146, v64, v48 offset0:136 offset1:168
	ds_write2_b32 v146, v65, v49 offset0:204 offset1:236
	v_subrev_u32_e32 v146, 0x1980, v146
	s_waitcnt lgkmcnt(0)
	ds_read_b128 v[34:37], v147
	ds_read_b128 v[38:41], v147 offset:16
	ds_read_b128 v[42:45], v147 offset:2176
	ds_read_b128 v[46:49], v147 offset:2192
	ds_read_b128 v[50:53], v147 offset:4352
	ds_read_b128 v[54:57], v147 offset:4368
	ds_read_b128 v[58:61], v147 offset:6528
	ds_read_b128 v[62:65], v147 offset:6544
	s_waitcnt lgkmcnt(6)
	v_mul_f32_e32 v170, 0xbfb8aa3b, v34
	v_mul_f32_e32 v171, 0xbfb8aa3b, v35
	v_mul_f32_e32 v172, 0xbfb8aa3b, v36
	v_mul_f32_e32 v173, 0xbfb8aa3b, v37
	v_exp_f32_e32 v170, v170
	v_exp_f32_e32 v171, v171
	v_exp_f32_e32 v172, v172
	v_exp_f32_e32 v173, v173
	v_add_f32_e32 v170, 1.0, v170
	v_add_f32_e32 v171, 1.0, v171
	v_add_f32_e32 v172, 1.0, v172
	v_add_f32_e32 v173, 1.0, v173
	v_rcp_f32_e32 v170, v170
	v_rcp_f32_e32 v171, v171
	v_rcp_f32_e32 v172, v172
	v_rcp_f32_e32 v173, v173
	s_nop 0
	v_mul_f32_e32 v34, v34, v170
	v_mul_f32_e32 v35, v35, v171
	v_mul_f32_e32 v36, v36, v172
	v_mul_f32_e32 v37, v37, v173
	v_cvt_pk_bf16_f32 v154, v34, v35
	v_cvt_pk_bf16_f32 v155, v36, v37
	v_mul_f32_e32 v170, 0xbfb8aa3b, v38
	v_mul_f32_e32 v171, 0xbfb8aa3b, v39
	v_mul_f32_e32 v172, 0xbfb8aa3b, v40
	v_mul_f32_e32 v173, 0xbfb8aa3b, v41
	v_exp_f32_e32 v170, v170
	v_exp_f32_e32 v171, v171
	v_exp_f32_e32 v172, v172
	v_exp_f32_e32 v173, v173
	v_add_f32_e32 v170, 1.0, v170
	v_add_f32_e32 v171, 1.0, v171
	v_add_f32_e32 v172, 1.0, v172
	v_add_f32_e32 v173, 1.0, v173
	v_rcp_f32_e32 v170, v170
	v_rcp_f32_e32 v171, v171
	v_rcp_f32_e32 v172, v172
	v_rcp_f32_e32 v173, v173
	s_nop 0
	v_mul_f32_e32 v38, v38, v170
	v_mul_f32_e32 v39, v39, v171
	v_mul_f32_e32 v40, v40, v172
	v_mul_f32_e32 v41, v41, v173
	v_cvt_pk_bf16_f32 v156, v38, v39
	v_cvt_pk_bf16_f32 v157, v40, v41
	global_store_dwordx4 v148, v[154:157], s[8:9]
	s_add_u32 s8, s8, 0xf000
	s_addc_u32 s9, s9, 0
	s_waitcnt lgkmcnt(4)
	v_mul_f32_e32 v170, 0xbfb8aa3b, v42
	v_mul_f32_e32 v171, 0xbfb8aa3b, v43
	v_mul_f32_e32 v172, 0xbfb8aa3b, v44
	v_mul_f32_e32 v173, 0xbfb8aa3b, v45
	v_exp_f32_e32 v170, v170
	v_exp_f32_e32 v171, v171
	v_exp_f32_e32 v172, v172
	v_exp_f32_e32 v173, v173
	v_add_f32_e32 v170, 1.0, v170
	v_add_f32_e32 v171, 1.0, v171
	v_add_f32_e32 v172, 1.0, v172
	v_add_f32_e32 v173, 1.0, v173
	v_rcp_f32_e32 v170, v170
	v_rcp_f32_e32 v171, v171
	v_rcp_f32_e32 v172, v172
	v_rcp_f32_e32 v173, v173
	s_nop 0
	v_mul_f32_e32 v42, v42, v170
	v_mul_f32_e32 v43, v43, v171
	v_mul_f32_e32 v44, v44, v172
	v_mul_f32_e32 v45, v45, v173
	v_cvt_pk_bf16_f32 v158, v42, v43
	v_cvt_pk_bf16_f32 v159, v44, v45
	v_mul_f32_e32 v170, 0xbfb8aa3b, v46
	v_mul_f32_e32 v171, 0xbfb8aa3b, v47
	v_mul_f32_e32 v172, 0xbfb8aa3b, v48
	v_mul_f32_e32 v173, 0xbfb8aa3b, v49
	v_exp_f32_e32 v170, v170
	v_exp_f32_e32 v171, v171
	v_exp_f32_e32 v172, v172
	v_exp_f32_e32 v173, v173
	v_add_f32_e32 v170, 1.0, v170
	v_add_f32_e32 v171, 1.0, v171
	v_add_f32_e32 v172, 1.0, v172
	v_add_f32_e32 v173, 1.0, v173
	v_rcp_f32_e32 v170, v170
	v_rcp_f32_e32 v171, v171
	v_rcp_f32_e32 v172, v172
	v_rcp_f32_e32 v173, v173
	s_nop 0
	v_mul_f32_e32 v46, v46, v170
	v_mul_f32_e32 v47, v47, v171
	v_mul_f32_e32 v48, v48, v172
	v_mul_f32_e32 v49, v49, v173
	v_cvt_pk_bf16_f32 v160, v46, v47
	v_cvt_pk_bf16_f32 v161, v48, v49
	global_store_dwordx4 v148, v[158:161], s[8:9]
	s_add_u32 s8, s8, 0xf000
	s_addc_u32 s9, s9, 0
	s_waitcnt lgkmcnt(2)
	v_mul_f32_e32 v170, 0xbfb8aa3b, v50
	v_mul_f32_e32 v171, 0xbfb8aa3b, v51
	v_mul_f32_e32 v172, 0xbfb8aa3b, v52
	v_mul_f32_e32 v173, 0xbfb8aa3b, v53
	v_exp_f32_e32 v170, v170
	v_exp_f32_e32 v171, v171
	v_exp_f32_e32 v172, v172
	v_exp_f32_e32 v173, v173
	v_add_f32_e32 v170, 1.0, v170
	v_add_f32_e32 v171, 1.0, v171
	v_add_f32_e32 v172, 1.0, v172
	v_add_f32_e32 v173, 1.0, v173
	v_rcp_f32_e32 v170, v170
	v_rcp_f32_e32 v171, v171
	v_rcp_f32_e32 v172, v172
	v_rcp_f32_e32 v173, v173
	s_nop 0
	v_mul_f32_e32 v50, v50, v170
	v_mul_f32_e32 v51, v51, v171
	v_mul_f32_e32 v52, v52, v172
	v_mul_f32_e32 v53, v53, v173
	v_cvt_pk_bf16_f32 v162, v50, v51
	v_cvt_pk_bf16_f32 v163, v52, v53
	v_mul_f32_e32 v170, 0xbfb8aa3b, v54
	v_mul_f32_e32 v171, 0xbfb8aa3b, v55
	v_mul_f32_e32 v172, 0xbfb8aa3b, v56
	v_mul_f32_e32 v173, 0xbfb8aa3b, v57
	v_exp_f32_e32 v170, v170
	v_exp_f32_e32 v171, v171
	v_exp_f32_e32 v172, v172
	v_exp_f32_e32 v173, v173
	v_add_f32_e32 v170, 1.0, v170
	v_add_f32_e32 v171, 1.0, v171
	v_add_f32_e32 v172, 1.0, v172
	v_add_f32_e32 v173, 1.0, v173
	v_rcp_f32_e32 v170, v170
	v_rcp_f32_e32 v171, v171
	v_rcp_f32_e32 v172, v172
	v_rcp_f32_e32 v173, v173
	s_nop 0
	v_mul_f32_e32 v54, v54, v170
	v_mul_f32_e32 v55, v55, v171
	v_mul_f32_e32 v56, v56, v172
	v_mul_f32_e32 v57, v57, v173
	v_cvt_pk_bf16_f32 v164, v54, v55
	v_cvt_pk_bf16_f32 v165, v56, v57
	global_store_dwordx4 v148, v[162:165], s[8:9]
	s_add_u32 s8, s8, 0xf000
	s_addc_u32 s9, s9, 0
	s_waitcnt lgkmcnt(0)
	v_mul_f32_e32 v170, 0xbfb8aa3b, v58
	v_mul_f32_e32 v171, 0xbfb8aa3b, v59
	v_mul_f32_e32 v172, 0xbfb8aa3b, v60
	v_mul_f32_e32 v173, 0xbfb8aa3b, v61
	v_exp_f32_e32 v170, v170
	v_exp_f32_e32 v171, v171
	v_exp_f32_e32 v172, v172
	v_exp_f32_e32 v173, v173
	v_add_f32_e32 v170, 1.0, v170
	v_add_f32_e32 v171, 1.0, v171
	v_add_f32_e32 v172, 1.0, v172
	v_add_f32_e32 v173, 1.0, v173
	v_rcp_f32_e32 v170, v170
	v_rcp_f32_e32 v171, v171
	v_rcp_f32_e32 v172, v172
	v_rcp_f32_e32 v173, v173
	s_nop 0
	v_mul_f32_e32 v58, v58, v170
	v_mul_f32_e32 v59, v59, v171
	v_mul_f32_e32 v60, v60, v172
	v_mul_f32_e32 v61, v61, v173
	v_cvt_pk_bf16_f32 v166, v58, v59
	v_cvt_pk_bf16_f32 v167, v60, v61
	v_mul_f32_e32 v170, 0xbfb8aa3b, v62
	v_mul_f32_e32 v171, 0xbfb8aa3b, v63
	v_mul_f32_e32 v172, 0xbfb8aa3b, v64
	v_mul_f32_e32 v173, 0xbfb8aa3b, v65
	v_exp_f32_e32 v170, v170
	v_exp_f32_e32 v171, v171
	v_exp_f32_e32 v172, v172
	v_exp_f32_e32 v173, v173
	v_add_f32_e32 v170, 1.0, v170
	v_add_f32_e32 v171, 1.0, v171
	v_add_f32_e32 v172, 1.0, v172
	v_add_f32_e32 v173, 1.0, v173
	v_rcp_f32_e32 v170, v170
	v_rcp_f32_e32 v171, v171
	v_rcp_f32_e32 v172, v172
	v_rcp_f32_e32 v173, v173
	s_nop 0
	v_mul_f32_e32 v62, v62, v170
	v_mul_f32_e32 v63, v63, v171
	v_mul_f32_e32 v64, v64, v172
	v_mul_f32_e32 v65, v65, v173
	v_cvt_pk_bf16_f32 v168, v62, v63
	v_cvt_pk_bf16_f32 v169, v64, v65
	global_store_dwordx4 v148, v[166:169], s[8:9]
	s_add_u32 s8, s8, 0xf000
	s_addc_u32 s9, s9, 0
	ds_write2_b32 v146, v18, v2 offset0:0 offset1:32
	ds_write2_b32 v146, v19, v3 offset0:68 offset1:100
	ds_write2_b32 v146, v20, v4 offset0:136 offset1:168
	ds_write2_b32 v146, v21, v5 offset0:204 offset1:236
	v_add_u32_e32 v146, 0x880, v146
	ds_write2_b32 v146, v22, v6 offset0:0 offset1:32
	ds_write2_b32 v146, v23, v7 offset0:68 offset1:100
	ds_write2_b32 v146, v24, v8 offset0:136 offset1:168
	ds_write2_b32 v146, v25, v9 offset0:204 offset1:236
	v_add_u32_e32 v146, 0x880, v146
	ds_write2_b32 v146, v26, v10 offset0:0 offset1:32
	ds_write2_b32 v146, v27, v11 offset0:68 offset1:100
	ds_write2_b32 v146, v28, v12 offset0:136 offset1:168
	ds_write2_b32 v146, v29, v13 offset0:204 offset1:236
	v_add_u32_e32 v146, 0x880, v146
	ds_write2_b32 v146, v30, v14 offset0:0 offset1:32
	ds_write2_b32 v146, v31, v15 offset0:68 offset1:100
	ds_write2_b32 v146, v32, v16 offset0:136 offset1:168
	ds_write2_b32 v146, v33, v17 offset0:204 offset1:236
	v_subrev_u32_e32 v146, 0x1980, v146
	s_waitcnt lgkmcnt(0)
	ds_read_b128 v[2:5], v147
	ds_read_b128 v[6:9], v147 offset:16
	ds_read_b128 v[10:13], v147 offset:2176
	ds_read_b128 v[14:17], v147 offset:2192
	ds_read_b128 v[18:21], v147 offset:4352
	ds_read_b128 v[22:25], v147 offset:4368
	ds_read_b128 v[26:29], v147 offset:6528
	ds_read_b128 v[30:33], v147 offset:6544
	s_waitcnt lgkmcnt(6)
	v_mul_f32_e32 v170, 0xbfb8aa3b, v2
	v_mul_f32_e32 v171, 0xbfb8aa3b, v3
	v_mul_f32_e32 v172, 0xbfb8aa3b, v4
	v_mul_f32_e32 v173, 0xbfb8aa3b, v5
	v_exp_f32_e32 v170, v170
	v_exp_f32_e32 v171, v171
	v_exp_f32_e32 v172, v172
	v_exp_f32_e32 v173, v173
	v_add_f32_e32 v170, 1.0, v170
	v_add_f32_e32 v171, 1.0, v171
	v_add_f32_e32 v172, 1.0, v172
	v_add_f32_e32 v173, 1.0, v173
	v_rcp_f32_e32 v170, v170
	v_rcp_f32_e32 v171, v171
	v_rcp_f32_e32 v172, v172
	v_rcp_f32_e32 v173, v173
	s_nop 0
	v_mul_f32_e32 v2, v2, v170
	v_mul_f32_e32 v3, v3, v171
	v_mul_f32_e32 v4, v4, v172
	v_mul_f32_e32 v5, v5, v173
	v_cvt_pk_bf16_f32 v154, v2, v3
	v_cvt_pk_bf16_f32 v155, v4, v5
	v_mul_f32_e32 v170, 0xbfb8aa3b, v6
	v_mul_f32_e32 v171, 0xbfb8aa3b, v7
	v_mul_f32_e32 v172, 0xbfb8aa3b, v8
	v_mul_f32_e32 v173, 0xbfb8aa3b, v9
	v_exp_f32_e32 v170, v170
	v_exp_f32_e32 v171, v171
	v_exp_f32_e32 v172, v172
	v_exp_f32_e32 v173, v173
	v_add_f32_e32 v170, 1.0, v170
	v_add_f32_e32 v171, 1.0, v171
	v_add_f32_e32 v172, 1.0, v172
	v_add_f32_e32 v173, 1.0, v173
	v_rcp_f32_e32 v170, v170
	v_rcp_f32_e32 v171, v171
	v_rcp_f32_e32 v172, v172
	v_rcp_f32_e32 v173, v173
	s_nop 0
	v_mul_f32_e32 v6, v6, v170
	v_mul_f32_e32 v7, v7, v171
	v_mul_f32_e32 v8, v8, v172
	v_mul_f32_e32 v9, v9, v173
	v_cvt_pk_bf16_f32 v156, v6, v7
	v_cvt_pk_bf16_f32 v157, v8, v9
	global_store_dwordx4 v148, v[154:157], s[8:9]
	s_add_u32 s8, s8, 0xf000
	s_addc_u32 s9, s9, 0
	s_waitcnt lgkmcnt(4)
	v_mul_f32_e32 v170, 0xbfb8aa3b, v10
	v_mul_f32_e32 v171, 0xbfb8aa3b, v11
	v_mul_f32_e32 v172, 0xbfb8aa3b, v12
	v_mul_f32_e32 v173, 0xbfb8aa3b, v13
	v_exp_f32_e32 v170, v170
	v_exp_f32_e32 v171, v171
	v_exp_f32_e32 v172, v172
	v_exp_f32_e32 v173, v173
	v_add_f32_e32 v170, 1.0, v170
	v_add_f32_e32 v171, 1.0, v171
	v_add_f32_e32 v172, 1.0, v172
	v_add_f32_e32 v173, 1.0, v173
	v_rcp_f32_e32 v170, v170
	v_rcp_f32_e32 v171, v171
	v_rcp_f32_e32 v172, v172
	v_rcp_f32_e32 v173, v173
	s_nop 0
	v_mul_f32_e32 v10, v10, v170
	v_mul_f32_e32 v11, v11, v171
	v_mul_f32_e32 v12, v12, v172
	v_mul_f32_e32 v13, v13, v173
	v_cvt_pk_bf16_f32 v158, v10, v11
	v_cvt_pk_bf16_f32 v159, v12, v13
	v_mul_f32_e32 v170, 0xbfb8aa3b, v14
	v_mul_f32_e32 v171, 0xbfb8aa3b, v15
	v_mul_f32_e32 v172, 0xbfb8aa3b, v16
	v_mul_f32_e32 v173, 0xbfb8aa3b, v17
	v_exp_f32_e32 v170, v170
	v_exp_f32_e32 v171, v171
	v_exp_f32_e32 v172, v172
	v_exp_f32_e32 v173, v173
	v_add_f32_e32 v170, 1.0, v170
	v_add_f32_e32 v171, 1.0, v171
	v_add_f32_e32 v172, 1.0, v172
	v_add_f32_e32 v173, 1.0, v173
	v_rcp_f32_e32 v170, v170
	v_rcp_f32_e32 v171, v171
	v_rcp_f32_e32 v172, v172
	v_rcp_f32_e32 v173, v173
	s_nop 0
	v_mul_f32_e32 v14, v14, v170
	v_mul_f32_e32 v15, v15, v171
	v_mul_f32_e32 v16, v16, v172
	v_mul_f32_e32 v17, v17, v173
	v_cvt_pk_bf16_f32 v160, v14, v15
	v_cvt_pk_bf16_f32 v161, v16, v17
	global_store_dwordx4 v148, v[158:161], s[8:9]
	s_add_u32 s8, s8, 0xf000
	s_addc_u32 s9, s9, 0
	s_waitcnt lgkmcnt(2)
	v_mul_f32_e32 v170, 0xbfb8aa3b, v18
	v_mul_f32_e32 v171, 0xbfb8aa3b, v19
	v_mul_f32_e32 v172, 0xbfb8aa3b, v20
	v_mul_f32_e32 v173, 0xbfb8aa3b, v21
	v_exp_f32_e32 v170, v170
	v_exp_f32_e32 v171, v171
	v_exp_f32_e32 v172, v172
	v_exp_f32_e32 v173, v173
	v_add_f32_e32 v170, 1.0, v170
	v_add_f32_e32 v171, 1.0, v171
	v_add_f32_e32 v172, 1.0, v172
	v_add_f32_e32 v173, 1.0, v173
	v_rcp_f32_e32 v170, v170
	v_rcp_f32_e32 v171, v171
	v_rcp_f32_e32 v172, v172
	v_rcp_f32_e32 v173, v173
	s_nop 0
	v_mul_f32_e32 v18, v18, v170
	v_mul_f32_e32 v19, v19, v171
	v_mul_f32_e32 v20, v20, v172
	v_mul_f32_e32 v21, v21, v173
	v_cvt_pk_bf16_f32 v162, v18, v19
	v_cvt_pk_bf16_f32 v163, v20, v21
	v_mul_f32_e32 v170, 0xbfb8aa3b, v22
	v_mul_f32_e32 v171, 0xbfb8aa3b, v23
	v_mul_f32_e32 v172, 0xbfb8aa3b, v24
	v_mul_f32_e32 v173, 0xbfb8aa3b, v25
	v_exp_f32_e32 v170, v170
	v_exp_f32_e32 v171, v171
	v_exp_f32_e32 v172, v172
	v_exp_f32_e32 v173, v173
	v_add_f32_e32 v170, 1.0, v170
	v_add_f32_e32 v171, 1.0, v171
	v_add_f32_e32 v172, 1.0, v172
	v_add_f32_e32 v173, 1.0, v173
	v_rcp_f32_e32 v170, v170
	v_rcp_f32_e32 v171, v171
	v_rcp_f32_e32 v172, v172
	v_rcp_f32_e32 v173, v173
	s_nop 0
	v_mul_f32_e32 v22, v22, v170
	v_mul_f32_e32 v23, v23, v171
	v_mul_f32_e32 v24, v24, v172
	v_mul_f32_e32 v25, v25, v173
	v_cvt_pk_bf16_f32 v164, v22, v23
	v_cvt_pk_bf16_f32 v165, v24, v25
	global_store_dwordx4 v148, v[162:165], s[8:9]
	s_add_u32 s8, s8, 0xf000
	s_addc_u32 s9, s9, 0
	s_waitcnt lgkmcnt(0)
	v_mul_f32_e32 v170, 0xbfb8aa3b, v26
	v_mul_f32_e32 v171, 0xbfb8aa3b, v27
	v_mul_f32_e32 v172, 0xbfb8aa3b, v28
	v_mul_f32_e32 v173, 0xbfb8aa3b, v29
	v_exp_f32_e32 v170, v170
	v_exp_f32_e32 v171, v171
	v_exp_f32_e32 v172, v172
	v_exp_f32_e32 v173, v173
	v_add_f32_e32 v170, 1.0, v170
	v_add_f32_e32 v171, 1.0, v171
	v_add_f32_e32 v172, 1.0, v172
	v_add_f32_e32 v173, 1.0, v173
	v_rcp_f32_e32 v170, v170
	v_rcp_f32_e32 v171, v171
	v_rcp_f32_e32 v172, v172
	v_rcp_f32_e32 v173, v173
	s_nop 0
	v_mul_f32_e32 v26, v26, v170
	v_mul_f32_e32 v27, v27, v171
	v_mul_f32_e32 v28, v28, v172
	v_mul_f32_e32 v29, v29, v173
	v_cvt_pk_bf16_f32 v166, v26, v27
	v_cvt_pk_bf16_f32 v167, v28, v29
	v_mul_f32_e32 v170, 0xbfb8aa3b, v30
	v_mul_f32_e32 v171, 0xbfb8aa3b, v31
	v_mul_f32_e32 v172, 0xbfb8aa3b, v32
	v_mul_f32_e32 v173, 0xbfb8aa3b, v33
	v_exp_f32_e32 v170, v170
	v_exp_f32_e32 v171, v171
	v_exp_f32_e32 v172, v172
	v_exp_f32_e32 v173, v173
	v_add_f32_e32 v170, 1.0, v170
	v_add_f32_e32 v171, 1.0, v171
	v_add_f32_e32 v172, 1.0, v172
	v_add_f32_e32 v173, 1.0, v173
	v_rcp_f32_e32 v170, v170
	v_rcp_f32_e32 v171, v171
	v_rcp_f32_e32 v172, v172
	v_rcp_f32_e32 v173, v173
	s_nop 0
	v_mul_f32_e32 v30, v30, v170
	v_mul_f32_e32 v31, v31, v171
	v_mul_f32_e32 v32, v32, v172
	v_mul_f32_e32 v33, v33, v173
	v_cvt_pk_bf16_f32 v168, v30, v31
	v_cvt_pk_bf16_f32 v169, v32, v33
	global_store_dwordx4 v148, v[166:169], s[8:9]
	s_add_u32 s8, s8, 0xf000
	s_addc_u32 s9, s9, 0
	s_add_i32 s70, s70, s10
	s_cmp_lt_i32 s70, s71
	s_waitcnt lgkmcnt(0)
	s_barrier
	s_cbranch_scc0 .LBB0_209
	s_branch .LBB0_215
